# v41 + gla3 item: the 8 dwordx2 loads of r (16 rows x 32 B) replaced by 4 fully coalesced dwordx4 loads re-laid out through a wave-private padded LDS scratch
# speedup vs baseline: 1.0130x; 1.0010x over previous
; #define LAS __attribute__((address_space(3)))
; __device__ __forceinline__ int otid() { int t = threadIdx.x; asm volatile("" : "+v"(t)); return t; }
; __device__ __forceinline__ void gla_issue_loads(GlaLoads& L, const bf16_t* proj, int b, int h, int n, int dk, int seg, int t4, bool want_q) {
; #pragma unroll
;     for (int i = 0; i < 16; ++i) { const int rb = n * 64 + seg * 16 + i, rc = rb < TB ? rb : TB - 1; const bf16_t* rp = proj + (size_t)(b * TB + rc) * NPROJ + h * 64 + dk;
;         L.xl[i] = rp[C_GL]; L.xk[i] = rp[C_K]; if (want_q) L.xq[i] = rp[C_Q]; }
; __device__ void gla3_item(const Params& p, int l, int item, LAS unsigned char* lds) {
;     const int t = otid(), half = t >> 8, t4 = t & 255, wv = (t >> 6) & 3, lane = t & 63, fr = lane & 15, fq = lane >> 4;
;     const int pair = item % (GCH / 2), bh = item / (GCH / 2), b = bh >> 2, h = bh & 3, n = pair * 2 + half;
;     bf16_t* proj = (bf16_t*)(p.ws + WS_PROJ);
;     LAS unsigned char* hl = lds + half * GL_HALF;
;     const int dk = t4 & 63, seg = t4 >> 6;
;     GlaLoads L; gla_issue_loads(L, proj, b, h, n, dk, seg, t4, true);
.LBB0_449:
	s_cmpk_gt_i32 s29, 0x1ff
	s_mov_b64 s[10:11], -1
	s_cbranch_scc0 .LBB0_523
	s_add_i32 s10, s29, 0xfe00
	s_and_b32 s11, s10, 0xffff
	s_mul_i32 s14, s11, 0xf83f
	s_lshr_b32 s11, s14, 21
	s_mul_i32 s15, s11, 33
	s_sub_i32 s10, s10, s15
	v_mov_b32_e32 v71, v228
	s_lshl_b32 s10, s10, 1
	s_bfe_u32 s15, s14, 0x20015
	v_ashrrev_i32_e32 v160, 8, v71
	s_and_b32 s10, s10, 0xfffe
	s_lshr_b32 s22, s14, 23
	s_waitcnt vmcnt(0)
	v_add_u32_e32 v2, s10, v160
	s_lshl_b32 s14, s15, 7
	v_and_b32_e32 v149, 63, v71
	s_lshl_b32 s100, s15, 8
	s_add_u32 s100, s3, s100
	s_addc_u32 s101, s18, 0
	v_lshlrev_b32_e32 v250, 2, v149
	global_load_dword v251, v250, s[100:101]
	v_bfe_u32 v74, v71, 6, 2
	v_lshlrev_b32_e32 v70, 6, v2
	s_add_u32 s40, s20, s14
	v_lshl_or_b32 v192, v74, 4, v70
	s_addc_u32 s41, s21, 0
	v_lshlrev_b32_e32 v0, 1, v149
	s_mul_i32 s10, s22, 0x1020
	v_lshl_add_u64 v[4:5], s[40:41], 0, v[0:1]
	v_min_i32_e32 v0, 0x101f, v192
	v_add_u32_e32 v0, s10, v0
	v_or_b32_e32 v189, 1, v192
	s_waitcnt lgkmcnt(0)
	v_mad_i64_i32 v[6:7], s[40:41], v0, s96, v[4:5]
	s_movk_i32 s22, 0x1000
	v_min_i32_e32 v0, 0x101f, v189
	v_add_co_u32_e32 v8, vcc, s22, v6
	v_add_u32_e32 v0, s10, v0
	v_or_b32_e32 v188, 2, v192
	v_addc_co_u32_e32 v9, vcc, 0, v7, vcc
	v_mad_i64_i32 v[10:11], s[40:41], v0, s96, v[4:5]
	v_min_i32_e32 v0, 0x101f, v188
	v_add_co_u32_e32 v12, vcc, s22, v10
	v_add_u32_e32 v0, s10, v0
	v_or_b32_e32 v186, 3, v192
	v_addc_co_u32_e32 v13, vcc, 0, v11, vcc
	v_mad_i64_i32 v[14:15], s[40:41], v0, s96, v[4:5]
	v_min_i32_e32 v0, 0x101f, v186
	global_load_ushort v193, v[8:9], off
	global_load_ushort v191, v[12:13], off
	global_load_ushort v148, v[14:15], off offset:1536
	global_load_ushort v150, v[14:15], off offset:1024
	global_load_ushort v157, v[10:11], off offset:1536
	global_load_ushort v158, v[10:11], off offset:1024
	global_load_ushort v159, v[6:7], off offset:1536
	global_load_ushort v161, v[6:7], off offset:1024
	v_add_co_u32_e32 v6, vcc, s22, v14
	v_add_u32_e32 v0, s10, v0
	v_or_b32_e32 v184, 4, v192
	v_addc_co_u32_e32 v7, vcc, 0, v15, vcc
	v_mad_i64_i32 v[8:9], s[40:41], v0, s96, v[4:5]
	v_min_i32_e32 v0, 0x101f, v184
	v_add_co_u32_e32 v10, vcc, s22, v8
	v_add_u32_e32 v0, s10, v0
	v_or_b32_e32 v182, 5, v192
	v_addc_co_u32_e32 v11, vcc, 0, v9, vcc
	v_mad_i64_i32 v[12:13], s[40:41], v0, s96, v[4:5]
	v_min_i32_e32 v0, 0x101f, v182
	v_add_co_u32_e32 v14, vcc, s22, v12
	v_add_u32_e32 v0, s10, v0
	v_or_b32_e32 v180, 6, v192
	v_addc_co_u32_e32 v15, vcc, 0, v13, vcc
	v_mad_i64_i32 v[16:17], s[40:41], v0, s96, v[4:5]
	v_min_i32_e32 v0, 0x101f, v180
	global_load_ushort v190, v[6:7], off
	global_load_ushort v187, v[10:11], off
	global_load_ushort v185, v[14:15], off
	global_load_ushort v143, v[16:17], off offset:1024
	global_load_ushort v145, v[12:13], off offset:1536
	global_load_ushort v147, v[12:13], off offset:1024
	global_load_ushort v152, v[8:9], off offset:1536
	global_load_ushort v156, v[8:9], off offset:1024
	v_add_co_u32_e32 v6, vcc, s22, v16
	v_add_u32_e32 v0, s10, v0
	v_or_b32_e32 v178, 7, v192
	v_addc_co_u32_e32 v7, vcc, 0, v17, vcc
	v_mad_i64_i32 v[8:9], s[40:41], v0, s96, v[4:5]
	v_min_i32_e32 v0, 0x101f, v178
	v_add_co_u32_e32 v10, vcc, s22, v8
	v_add_u32_e32 v0, s10, v0
	v_or_b32_e32 v176, 8, v192
	v_addc_co_u32_e32 v11, vcc, 0, v9, vcc
	v_mad_i64_i32 v[12:13], s[40:41], v0, s96, v[4:5]
	v_min_i32_e32 v0, 0x101f, v176
	v_add_co_u32_e32 v14, vcc, s22, v12
	v_add_u32_e32 v0, s10, v0
	v_or_b32_e32 v173, 9, v192
	v_addc_co_u32_e32 v15, vcc, 0, v13, vcc
	global_load_ushort v183, v[6:7], off
	global_load_ushort v181, v[10:11], off
	global_load_ushort v179, v[14:15], off
	global_load_ushort v134, v[12:13], off offset:1536
	global_load_ushort v136, v[12:13], off offset:1024
	global_load_ushort v138, v[8:9], off offset:1536
	global_load_ushort v140, v[8:9], off offset:1024
	global_load_ushort v146, v[16:17], off offset:1536
	v_mad_i64_i32 v[6:7], s[40:41], v0, s96, v[4:5]
	v_min_i32_e32 v0, 0x101f, v173
	v_add_co_u32_e32 v8, vcc, s22, v6
	v_add_u32_e32 v0, s10, v0
	v_or_b32_e32 v172, 10, v192
	v_addc_co_u32_e32 v9, vcc, 0, v7, vcc
	v_mad_i64_i32 v[10:11], s[40:41], v0, s96, v[4:5]
	v_min_i32_e32 v0, 0x101f, v172
	v_add_co_u32_e32 v12, vcc, s22, v10
	v_add_u32_e32 v0, s10, v0
	v_or_b32_e32 v170, 11, v192
	v_addc_co_u32_e32 v13, vcc, 0, v11, vcc
	v_mad_i64_i32 v[14:15], s[40:41], v0, s96, v[4:5]
	v_min_i32_e32 v0, 0x101f, v170
	global_load_ushort v177, v[8:9], off
	global_load_ushort v175, v[12:13], off
	global_load_ushort v121, v[14:15], off offset:1536
	global_load_ushort v125, v[14:15], off offset:1024
	global_load_ushort v128, v[10:11], off offset:1536
	global_load_ushort v133, v[10:11], off offset:1024
	global_load_ushort v135, v[6:7], off offset:1536
	global_load_ushort v137, v[6:7], off offset:1024
	v_add_co_u32_e32 v6, vcc, s22, v14
	v_add_u32_e32 v0, s10, v0
	v_or_b32_e32 v168, 12, v192
	v_addc_co_u32_e32 v7, vcc, 0, v15, vcc
	v_mad_i64_i32 v[8:9], s[40:41], v0, s96, v[4:5]
	v_min_i32_e32 v0, 0x101f, v168
	v_add_co_u32_e32 v10, vcc, s22, v8
	v_add_u32_e32 v0, s10, v0
	v_or_b32_e32 v166, 13, v192
	v_addc_co_u32_e32 v11, vcc, 0, v9, vcc
	v_mad_i64_i32 v[12:13], s[40:41], v0, s96, v[4:5]
	v_min_i32_e32 v0, 0x101f, v166
	v_add_co_u32_e32 v14, vcc, s22, v12
	v_add_u32_e32 v0, s10, v0
	v_or_b32_e32 v164, 14, v192
	v_addc_co_u32_e32 v15, vcc, 0, v13, vcc
	v_mad_i64_i32 v[16:17], s[40:41], v0, s96, v[4:5]
	v_min_i32_e32 v0, 0x101f, v164
	global_load_ushort v174, v[6:7], off
	global_load_ushort v171, v[10:11], off
	global_load_ushort v169, v[14:15], off
	global_load_ushort v106, v[16:17], off offset:1024
	global_load_ushort v110, v[12:13], off offset:1536
; __device__ __forceinline__ void gla_issue_loads(GlaLoads& L, const bf16_t* proj, int b, int h, int n, int dk, int seg, int t4, bool want_q) {
; #pragma unroll
;     for (int i = 0; i < 16; ++i) { const int rb = n * 64 + seg * 16 + i, rc = rb < TB ? rb : TB - 1; const bf16_t* rp = proj + (size_t)(b * TB + rc) * NPROJ + h * 64 + dk;
;         L.xl[i] = rp[C_GL]; L.xk[i] = rp[C_K]; if (want_q) L.xq[i] = rp[C_Q]; }
; #pragma unroll
;     for (int q = 0; q < 4; ++q) { const int task = t4 + 256 * q, dv = task & 127, rg = task >> 7;
; #pragma unroll
;         for (int j = 0; j < 8; ++j) { const int rb = n * 64 + rg * 8 + j, rc = rb < TB ? rb : TB - 1; L.vv[q][j] = proj[(size_t)(b * TB + rc) * NPROJ + C_V + h * 128 + dv]; } }
	global_load_ushort v119, v[12:13], off offset:1024
	global_load_ushort v126, v[8:9], off offset:1536
	global_load_ushort v127, v[8:9], off offset:1024
	v_add_co_u32_e32 v6, vcc, s22, v16
	v_add_u32_e32 v0, s10, v0
	v_or_b32_e32 v162, 15, v192
	v_addc_co_u32_e32 v7, vcc, 0, v17, vcc
	v_mad_i64_i32 v[8:9], s[40:41], v0, s96, v[4:5]
	v_min_i32_e32 v0, 0x101f, v162
	v_add_co_u32_e32 v10, vcc, s22, v8
	v_add_u32_e32 v0, s10, v0
	s_nop 0
	v_addc_co_u32_e32 v11, vcc, 0, v9, vcc
	v_mad_i64_i32 v[4:5], s[40:41], v0, s96, v[4:5]
	v_lshrrev_b32_e32 v0, 4, v71
	v_add_co_u32_e32 v12, vcc, s22, v4
	v_and_or_b32 v3, v0, 8, v70
	s_nop 0
	v_addc_co_u32_e32 v13, vcc, 0, v5, vcc
	global_load_ushort v167, v[6:7], off
	global_load_ushort v165, v[10:11], off
	global_load_ushort v163, v[12:13], off
	global_load_ushort v73, v[4:5], off offset:1536
	global_load_ushort v78, v[4:5], off offset:1024
	global_load_ushort v81, v[8:9], off offset:1536
	global_load_ushort v104, v[8:9], off offset:1024
	global_load_ushort v112, v[16:17], off offset:1536
	v_or_b32_e32 v6, 1, v3
	v_or_b32_e32 v8, 2, v3
	v_or_b32_e32 v10, 3, v3
	v_or_b32_e32 v12, 4, v3
	v_or_b32_e32 v14, 5, v3
	v_or_b32_e32 v16, 6, v3
	v_min_i32_e32 v0, 0x101f, v3
	v_min_i32_e32 v6, 0x101f, v6
	v_min_i32_e32 v8, 0x101f, v8
	v_min_i32_e32 v10, 0x101f, v10
	v_min_i32_e32 v12, 0x101f, v12
	v_min_i32_e32 v14, 0x101f, v14
	v_min_i32_e32 v16, 0x101f, v16
	v_or_b32_e32 v18, 7, v3
	v_add_u32_e32 v0, s10, v0
	v_mov_b64_e32 v[68:69], s[20:21]
	v_add_u32_e32 v6, s10, v6
	v_add_u32_e32 v8, s10, v8
	v_add_u32_e32 v10, s10, v10
	v_add_u32_e32 v12, s10, v12
	v_add_u32_e32 v14, s10, v14
	v_add_u32_e32 v16, s10, v16
	v_min_i32_e32 v18, 0x101f, v18
	v_and_b32_e32 v72, 0x7f, v71
	v_mad_i64_i32 v[4:5], s[40:41], v0, s96, v[68:69]
	s_lshl_b32 s86, s15, 8
	v_mad_i64_i32 v[6:7], s[40:41], v6, s96, v[68:69]
	v_mad_i64_i32 v[8:9], s[40:41], v8, s96, v[68:69]
	v_mad_i64_i32 v[10:11], s[40:41], v10, s96, v[68:69]
	v_mad_i64_i32 v[12:13], s[40:41], v12, s96, v[68:69]
	v_mad_i64_i32 v[14:15], s[40:41], v14, s96, v[68:69]
	v_mad_i64_i32 v[16:17], s[40:41], v16, s96, v[68:69]
	v_add_u32_e32 v18, s10, v18
	v_lshl_add_u64 v[4:5], v[4:5], 0, s[86:87]
	v_lshlrev_b32_e32 v0, 1, v72
	v_lshl_add_u64 v[6:7], v[6:7], 0, s[86:87]
	v_lshl_add_u64 v[8:9], v[8:9], 0, s[86:87]
	v_lshl_add_u64 v[10:11], v[10:11], 0, s[86:87]
	v_lshl_add_u64 v[12:13], v[12:13], 0, s[86:87]
	v_lshl_add_u64 v[14:15], v[14:15], 0, s[86:87]
	v_lshl_add_u64 v[16:17], v[16:17], 0, s[86:87]
	v_mad_i64_i32 v[18:19], s[40:41], v18, s96, v[68:69]
	v_lshl_add_u64 v[4:5], v[4:5], 0, v[0:1]
	v_lshl_add_u64 v[6:7], v[6:7], 0, v[0:1]
	v_lshl_add_u64 v[8:9], v[8:9], 0, v[0:1]
	v_lshl_add_u64 v[10:11], v[10:11], 0, v[0:1]
	v_lshl_add_u64 v[12:13], v[12:13], 0, v[0:1]
	v_lshl_add_u64 v[14:15], v[14:15], 0, v[0:1]
	v_lshl_add_u64 v[16:17], v[16:17], 0, v[0:1]
	v_lshl_add_u64 v[18:19], v[18:19], 0, s[86:87]
	v_lshl_add_u64 v[18:19], v[18:19], 0, v[0:1]
	global_load_ushort v114, v[4:5], off offset:2048
	global_load_ushort v102, v[6:7], off offset:2048
	global_load_ushort v115, v[8:9], off offset:2048
	global_load_ushort v101, v[10:11], off offset:2048
	global_load_ushort v116, v[12:13], off offset:2048
	global_load_ushort v80, v[14:15], off offset:2048
	global_load_ushort v117, v[16:17], off offset:2048
	global_load_ushort v79, v[18:19], off offset:2048
	v_or_b32_e32 v4, 16, v3
	v_or_b32_e32 v6, 17, v3
	v_or_b32_e32 v8, 18, v3
	v_or_b32_e32 v10, 19, v3
	v_or_b32_e32 v12, 20, v3
	v_or_b32_e32 v14, 21, v3
	v_or_b32_e32 v16, 22, v3
	v_min_i32_e32 v4, 0x101f, v4
	v_min_i32_e32 v6, 0x101f, v6
	v_min_i32_e32 v8, 0x101f, v8
	v_min_i32_e32 v10, 0x101f, v10
	v_min_i32_e32 v12, 0x101f, v12
	v_min_i32_e32 v14, 0x101f, v14
	v_min_i32_e32 v16, 0x101f, v16
	v_or_b32_e32 v18, 23, v3
	v_add_u32_e32 v4, s10, v4
	v_add_u32_e32 v6, s10, v6
	v_add_u32_e32 v8, s10, v8
	v_add_u32_e32 v10, s10, v10
	v_add_u32_e32 v12, s10, v12
	v_add_u32_e32 v14, s10, v14
	v_add_u32_e32 v16, s10, v16
	v_min_i32_e32 v18, 0x101f, v18
	v_mad_i64_i32 v[4:5], s[40:41], v4, s96, v[68:69]
	v_mad_i64_i32 v[6:7], s[40:41], v6, s96, v[68:69]
	v_mad_i64_i32 v[8:9], s[40:41], v8, s96, v[68:69]
	v_mad_i64_i32 v[10:11], s[40:41], v10, s96, v[68:69]
	v_mad_i64_i32 v[12:13], s[40:41], v12, s96, v[68:69]
	v_mad_i64_i32 v[14:15], s[40:41], v14, s96, v[68:69]
	v_mad_i64_i32 v[16:17], s[40:41], v16, s96, v[68:69]
	v_add_u32_e32 v18, s10, v18
	v_lshl_add_u64 v[4:5], v[4:5], 0, s[86:87]
	v_lshl_add_u64 v[6:7], v[6:7], 0, s[86:87]
	v_lshl_add_u64 v[8:9], v[8:9], 0, s[86:87]
	v_lshl_add_u64 v[10:11], v[10:11], 0, s[86:87]
	v_lshl_add_u64 v[12:13], v[12:13], 0, s[86:87]
	v_lshl_add_u64 v[14:15], v[14:15], 0, s[86:87]
	v_lshl_add_u64 v[16:17], v[16:17], 0, s[86:87]
	v_mad_i64_i32 v[18:19], s[40:41], v18, s96, v[68:69]
	v_lshl_add_u64 v[4:5], v[4:5], 0, v[0:1]
	v_lshl_add_u64 v[6:7], v[6:7], 0, v[0:1]
	v_lshl_add_u64 v[8:9], v[8:9], 0, v[0:1]
	v_lshl_add_u64 v[10:11], v[10:11], 0, v[0:1]
	v_lshl_add_u64 v[12:13], v[12:13], 0, v[0:1]
	v_lshl_add_u64 v[14:15], v[14:15], 0, v[0:1]
	v_lshl_add_u64 v[16:17], v[16:17], 0, v[0:1]
	v_lshl_add_u64 v[18:19], v[18:19], 0, s[86:87]
	v_lshl_add_u64 v[18:19], v[18:19], 0, v[0:1]
	global_load_ushort v129, v[4:5], off offset:2048
	global_load_ushort v108, v[6:7], off offset:2048
	global_load_ushort v130, v[8:9], off offset:2048
	global_load_ushort v107, v[10:11], off offset:2048
	global_load_ushort v131, v[12:13], off offset:2048
	global_load_ushort v105, v[14:15], off offset:2048
	global_load_ushort v132, v[16:17], off offset:2048
	global_load_ushort v103, v[18:19], off offset:2048
	v_or_b32_e32 v4, 32, v3
; __device__ __forceinline__ void gla_issue_loads(GlaLoads& L, const bf16_t* proj, int b, int h, int n, int dk, int seg, int t4, bool want_q) {
;     ...
;     for (int q = 0; q < 4; ++q) { const int task = t4 + 256 * q, dv = task & 127, rg = task >> 7;
; #pragma unroll
;         for (int j = 0; j < 8; ++j) { const int rb = n * 64 + rg * 8 + j, rc = rb < TB ? rb : TB - 1; L.vv[q][j] = proj[(size_t)(b * TB + rc) * NPROJ + C_V + h * 128 + dv]; } }
; __device__ void gla3_item(const Params& p, int l, int item, LAS unsigned char* lds) {
;     ...
;     const bf16_t* spT = (const bf16_t*)((const unsigned char*)p.out + OS_KVT) + ((size_t)bh * GCH + n) * 8192;
;     bf16x8 spf[8][2];
; #pragma unroll
;     for (int nt = 0; nt < 8; ++nt)
; #pragma unroll
;         for (int ks = 0; ks < 2; ++ks) spf[nt][ks] = *(const bf16x8*)(spT + (nt * 16 + fr) * 64 + ks * 32 + fq * 8);
	v_or_b32_e32 v6, 33, v3
	v_or_b32_e32 v8, 34, v3
	v_or_b32_e32 v10, 35, v3
	v_or_b32_e32 v12, 36, v3
	v_or_b32_e32 v14, 37, v3
	v_or_b32_e32 v16, 38, v3
	v_min_i32_e32 v4, 0x101f, v4
	v_min_i32_e32 v6, 0x101f, v6
	v_min_i32_e32 v8, 0x101f, v8
	v_min_i32_e32 v10, 0x101f, v10
	v_min_i32_e32 v12, 0x101f, v12
	v_min_i32_e32 v14, 0x101f, v14
	v_min_i32_e32 v16, 0x101f, v16
	v_or_b32_e32 v18, 39, v3
	v_add_u32_e32 v4, s10, v4
	v_add_u32_e32 v6, s10, v6
	v_add_u32_e32 v8, s10, v8
	v_add_u32_e32 v10, s10, v10
	v_add_u32_e32 v12, s10, v12
	v_add_u32_e32 v14, s10, v14
	v_add_u32_e32 v16, s10, v16
	v_min_i32_e32 v18, 0x101f, v18
	v_mad_i64_i32 v[4:5], s[40:41], v4, s96, v[68:69]
	v_mad_i64_i32 v[6:7], s[40:41], v6, s96, v[68:69]
	v_mad_i64_i32 v[8:9], s[40:41], v8, s96, v[68:69]
	v_mad_i64_i32 v[10:11], s[40:41], v10, s96, v[68:69]
	v_mad_i64_i32 v[12:13], s[40:41], v12, s96, v[68:69]
	v_mad_i64_i32 v[14:15], s[40:41], v14, s96, v[68:69]
	v_mad_i64_i32 v[16:17], s[40:41], v16, s96, v[68:69]
	v_add_u32_e32 v18, s10, v18
	v_lshl_add_u64 v[4:5], v[4:5], 0, s[86:87]
	v_lshl_add_u64 v[6:7], v[6:7], 0, s[86:87]
	v_lshl_add_u64 v[8:9], v[8:9], 0, s[86:87]
	v_lshl_add_u64 v[10:11], v[10:11], 0, s[86:87]
	v_lshl_add_u64 v[12:13], v[12:13], 0, s[86:87]
	v_lshl_add_u64 v[14:15], v[14:15], 0, s[86:87]
	v_lshl_add_u64 v[16:17], v[16:17], 0, s[86:87]
	v_mad_i64_i32 v[18:19], s[40:41], v18, s96, v[68:69]
	v_lshl_add_u64 v[4:5], v[4:5], 0, v[0:1]
	v_lshl_add_u64 v[6:7], v[6:7], 0, v[0:1]
	v_lshl_add_u64 v[8:9], v[8:9], 0, v[0:1]
	v_lshl_add_u64 v[10:11], v[10:11], 0, v[0:1]
	v_lshl_add_u64 v[12:13], v[12:13], 0, v[0:1]
	v_lshl_add_u64 v[14:15], v[14:15], 0, v[0:1]
	v_lshl_add_u64 v[16:17], v[16:17], 0, v[0:1]
	v_lshl_add_u64 v[18:19], v[18:19], 0, s[86:87]
	v_lshl_add_u64 v[18:19], v[18:19], 0, v[0:1]
	global_load_ushort v139, v[4:5], off offset:2048
	global_load_ushort v118, v[6:7], off offset:2048
	global_load_ushort v141, v[8:9], off offset:2048
	global_load_ushort v113, v[10:11], off offset:2048
	global_load_ushort v142, v[12:13], off offset:2048
	global_load_ushort v111, v[14:15], off offset:2048
	global_load_ushort v144, v[16:17], off offset:2048
	global_load_ushort v109, v[18:19], off offset:2048
	v_or_b32_e32 v4, 48, v3
	v_or_b32_e32 v6, 49, v3
	v_or_b32_e32 v8, 50, v3
	v_or_b32_e32 v10, 51, v3
	v_or_b32_e32 v12, 52, v3
	v_or_b32_e32 v14, 53, v3
	v_or_b32_e32 v16, 54, v3
	v_or_b32_e32 v3, 55, v3
	v_min_i32_e32 v4, 0x101f, v4
	v_min_i32_e32 v6, 0x101f, v6
	v_min_i32_e32 v8, 0x101f, v8
	v_min_i32_e32 v10, 0x101f, v10
	v_min_i32_e32 v12, 0x101f, v12
	v_min_i32_e32 v14, 0x101f, v14
	v_min_i32_e32 v16, 0x101f, v16
	v_min_i32_e32 v3, 0x101f, v3
	v_add_u32_e32 v4, s10, v4
	v_add_u32_e32 v6, s10, v6
	v_add_u32_e32 v8, s10, v8
	v_add_u32_e32 v10, s10, v10
	v_add_u32_e32 v12, s10, v12
	v_add_u32_e32 v14, s10, v14
	v_add_u32_e32 v16, s10, v16
	v_add_u32_e32 v3, s10, v3
	v_mad_i64_i32 v[4:5], s[40:41], v4, s96, v[68:69]
	v_mad_i64_i32 v[6:7], s[40:41], v6, s96, v[68:69]
	v_mad_i64_i32 v[8:9], s[40:41], v8, s96, v[68:69]
	v_mad_i64_i32 v[10:11], s[40:41], v10, s96, v[68:69]
	v_mad_i64_i32 v[12:13], s[40:41], v12, s96, v[68:69]
	v_mad_i64_i32 v[14:15], s[40:41], v14, s96, v[68:69]
	v_mad_i64_i32 v[16:17], s[40:41], v16, s96, v[68:69]
	v_mad_i64_i32 v[18:19], s[40:41], v3, s96, v[68:69]
	s_mul_i32 s40, s11, 0x42
	s_mov_b32 s41, s87
	v_ashrrev_i32_e32 v3, 31, v2
	v_lshl_add_u64 v[2:3], v[2:3], 0, s[40:41]
	v_lshl_add_u64 v[4:5], v[4:5], 0, s[86:87]
	v_lshlrev_b64 v[2:3], 14, v[2:3]
	v_and_b32_e32 v75, 15, v71
	v_lshl_add_u64 v[4:5], v[4:5], 0, v[0:1]
	v_lshl_add_u64 v[6:7], v[6:7], 0, s[86:87]
	v_lshl_add_u64 v[8:9], v[8:9], 0, s[86:87]
	v_lshl_add_u64 v[10:11], v[10:11], 0, s[86:87]
	v_lshl_add_u64 v[12:13], v[12:13], 0, s[86:87]
	v_lshl_add_u64 v[14:15], v[14:15], 0, s[86:87]
	v_lshl_add_u64 v[16:17], v[16:17], 0, s[86:87]
	v_lshl_add_u64 v[18:19], v[18:19], 0, s[86:87]
	v_lshl_add_u64 v[2:3], s[16:17], 0, v[2:3]
	v_bfe_u32 v240, v228, 6, 2
	v_lshlrev_b32_e32 v240, 12, v240
	v_and_b32_e32 v241, 63, v228
	v_lshl_or_b32 v240, v241, 4, v240
	v_mov_b32_e32 v241, 0
	v_lshl_add_u64 v[242:243], v[2:3], 0, v[240:241]
	v_and_b32_e32 v66, 48, v71
	v_mov_b32_e32 v67, v1
	v_lshl_add_u64 v[6:7], v[6:7], 0, v[0:1]
	v_lshl_add_u64 v[8:9], v[8:9], 0, v[0:1]
	v_lshl_add_u64 v[10:11], v[10:11], 0, v[0:1]
; __device__ __forceinline__ float bf2f(bf16_t b) { return __uint_as_float(((unsigned)b) << 16); }
; __device__ __forceinline__ float logsigmoidf_(float x) { return fminf(x, 0.f) - __logf(1.0f + __expf(-fabsf(x))); }
; __device__ __forceinline__ float gla_cumsum(const Params& p, int l, const GlaLoads& L, int h, int n, int dk, int seg, LAS unsigned char* hl, float (&bc)[16]) {
;     const float ba = p.b_alpha[(size_t)l * 256 + h * 64 + dk]; float run = 0.f;
; #pragma unroll
;     for (int i = 0; i < 16; ++i) { const int rb = n * 64 + seg * 16 + i; const float la = rb < TB ? logsigmoidf_(bf2f(L.xl[i]) + ba) * (1.0f / 16.0f) : 0.f;
;         run += la; bc[i] = run; }
; __device__ void gla3_item(const Params& p, int l, int item, LAS unsigned char* lds) {
;     ...
;     const int rb = n * 64 + wv * 16 + fr, rbc = rb < TB ? rb : TB - 1;
;     bf16_t* rowp = proj + (size_t)(b * TB + rbc) * NPROJ;
;     u32x2 rwv[8];
; #pragma unroll
;     for (int nt = 0; nt < 8; ++nt) rwv[nt] = *(const u32x2*)(rowp + C_R + h * 128 + nt * 16 + 4 * fq);
	v_lshl_add_u64 v[12:13], v[12:13], 0, v[0:1]
	v_lshl_add_u64 v[14:15], v[14:15], 0, v[0:1]
	v_lshl_add_u64 v[16:17], v[16:17], 0, v[0:1]
	v_lshl_add_u64 v[18:19], v[18:19], 0, v[0:1]
	global_load_ushort v154, v[4:5], off offset:2048
	global_load_ushort v124, v[6:7], off offset:2048
	global_load_ushort v155, v[8:9], off offset:2048
	global_load_ushort v123, v[10:11], off offset:2048
	global_load_ushort v151, v[12:13], off offset:2048
	global_load_ushort v122, v[14:15], off offset:2048
	global_load_ushort v153, v[16:17], off offset:2048
	global_load_ushort v120, v[18:19], off offset:2048
	v_lshl_add_u64 v[2:3], v[2:3], 0, v[66:67]
	v_lshlrev_b32_e32 v4, 7, v75
	v_mov_b32_e32 v5, v1
	v_lshl_add_u64 v[2:3], v[2:3], 0, v[4:5]
	v_add_co_u32_e32 v4, vcc, s22, v2
	s_movk_i32 s11, 0x2000
	s_nop 0
	v_addc_co_u32_e32 v5, vcc, 0, v3, vcc
	v_add_co_u32_e32 v46, vcc, s11, v2
	s_movk_i32 s11, 0x3000
	s_nop 0
	v_addc_co_u32_e32 v47, vcc, 0, v3, vcc
	global_load_dwordx4 v[204:207], v[242:243], off
	global_load_dwordx4 v[208:211], v[242:243], off offset:1024
	global_load_dwordx4 v[212:215], v[242:243], off offset:2048
	global_load_dwordx4 v[216:219], v[242:243], off offset:3072
	v_add_co_u32_e32 v2, vcc, s11, v2
	v_lshl_or_b32 v77, v74, 4, v75
	s_nop 0
	v_addc_co_u32_e32 v3, vcc, 0, v3, vcc
	v_or_b32_e32 v67, v77, v70
	s_movk_i32 s22, 0x1020
	v_cmp_gt_i32_e32 vcc, s22, v67
	v_mov_b32_e32 v82, 0x101f
	v_bfe_u32 v76, v71, 4, 2
	v_cndmask_b32_e32 v67, v82, v67, vcc
	v_add_u32_e32 v67, s10, v67
	v_and_b32_e32 v240, 15, v228
	v_lshlrev_b32_e32 v240, 4, v240
	v_mov_b32_e32 v241, 0
	v_bfe_u32 v243, v228, 6, 2
	v_lshl_add_u32 v243, v243, 4, v70
	v_bfe_u32 v242, v228, 4, 2
	v_add_u32_e32 v243, v243, v242
	v_mov_b32_e32 v242, v243
	v_min_i32_e32 v242, 0x101f, v242
	v_add_u32_e32 v242, s10, v242
	v_mad_i64_i32 v[246:247], s[100:101], v242, s96, v[68:69]
	v_lshl_add_u64 v[246:247], v[246:247], 0, s[86:87]
	v_lshl_add_u64 v[246:247], v[246:247], 0, v[240:241]
	global_load_dwordx4 v[50:53], v[246:247], off offset:3072
	v_add_u32_e32 v242, 4, v243
	v_min_i32_e32 v242, 0x101f, v242
	v_add_u32_e32 v242, s10, v242
	v_mad_i64_i32 v[246:247], s[100:101], v242, s96, v[68:69]
	v_lshl_add_u64 v[246:247], v[246:247], 0, s[86:87]
	v_lshl_add_u64 v[246:247], v[246:247], 0, v[240:241]
	global_load_dwordx4 v[54:57], v[246:247], off offset:3072
	v_add_u32_e32 v242, 8, v243
	v_min_i32_e32 v242, 0x101f, v242
	v_add_u32_e32 v242, s10, v242
	v_mad_i64_i32 v[246:247], s[100:101], v242, s96, v[68:69]
	v_lshl_add_u64 v[246:247], v[246:247], 0, s[86:87]
	v_lshl_add_u64 v[246:247], v[246:247], 0, v[240:241]
	global_load_dwordx4 v[58:61], v[246:247], off offset:3072
	v_add_u32_e32 v242, 12, v243
	v_min_i32_e32 v242, 0x101f, v242
	v_add_u32_e32 v242, s10, v242
	v_mad_i64_i32 v[246:247], s[100:101], v242, s96, v[68:69]
	v_lshl_add_u64 v[246:247], v[246:247], 0, s[86:87]
	v_lshl_add_u64 v[246:247], v[246:247], 0, v[240:241]
	global_load_dwordx4 v[62:65], v[246:247], off offset:3072
	v_mad_i64_i32 v[68:69], s[10:11], v67, s96, v[68:69]
	v_lshlrev_b32_e32 v0, 3, v76
	v_lshl_add_u64 v[68:69], v[68:69], 0, s[86:87]
	v_lshl_add_u64 v[82:83], v[68:69], 0, v[0:1]
	s_nop 0
	s_nop 0
	s_nop 0
	s_add_u32 s10, s3, s86
	s_addc_u32 s11, s18, 0
	v_lshlrev_b32_e32 v100, 2, v149
	s_barrier
	s_waitcnt vmcnt(40)
	v_mov_b32_e32 v69, v251
	s_movk_i32 s15, 0x1020
	v_cmp_gt_i32_e64 s[40:41], s22, v192
	v_mov_b32_e32 v67, 0
	v_mov_b32_e32 v68, 0
	s_and_saveexec_b64 s[10:11], s[40:41]
	s_cbranch_execz .LBB0_452
	v_lshlrev_b32_e32 v68, 16, v193
	v_add_f32_e32 v68, v69, v68
	s_mov_b32 s22, 0xbfb8aa3b
	v_mul_f32_e64 v192, |v68|, s22
	v_exp_f32_e32 v192, v192
	s_mov_b32 s22, 0x800000
	v_min_f32_e32 v68, 0, v68
	v_add_f32_e32 v192, 1.0, v192
	v_cmp_gt_f32_e64 s[42:43], s22, v192
	s_mov_b32 s22, 0x3f317217
	s_nop 0
	v_cndmask_b32_e64 v193, 0, 32, s[42:43]
	v_ldexp_f32 v192, v192, v193
	v_log_f32_e32 v192, v192
	s_nop 0
	v_mul_f32_e32 v193, 0x3f317217, v192
	v_fma_f32 v193, v192, s22, -v193
	v_fmac_f32_e32 v193, 0x3377d1cf, v192
	s_mov_b32 s22, 0x7f800000
	v_fmac_f32_e32 v193, 0x3f317217, v192
	v_cmp_lt_f32_e64 s[44:45], |v192|, s22
	s_mov_b32 s22, 0x3d800000
	s_nop 0
	v_cndmask_b32_e64 v192, v192, v193, s[44:45]
	v_cndmask_b32_e64 v193, 0, v236, s[42:43]
	v_sub_f32_e32 v192, v192, v193
	v_sub_f32_e32 v68, v68, v192
	v_fma_f32 v68, v68, s22, 0

; #define LAS __attribute__((address_space(3)))
; __device__ __forceinline__ float gla_cumsum(const Params& p, int l, const GlaLoads& L, int h, int n, int dk, int seg, LAS unsigned char* hl, float (&bc)[16]) {
;     ...
;     LAS float* segs = (LAS float*)(hl + GL_SEG);
;     segs[seg * 64 + dk] = run;
;     __syncthreads();
;     float pre = 0.f, tot = 0.f;
; #pragma unroll
;     for (int s = 0; s < 4; ++s) { const float v = segs[s * 64 + dk]; tot += v; if (s < seg) pre += v; }
; #pragma unroll
;     for (int i = 0; i < 16; ++i) bc[i] += pre;
; __device__ void gla3_item(const Params& p, int l, int item, LAS unsigned char* lds) {
;     ...
;     const int rb = n * 64 + wv * 16 + fr, rbc = rb < TB ? rb : TB - 1;
;     bf16_t* rowp = proj + (size_t)(b * TB + rbc) * NPROJ;
;     u32x2 rwv[8];
; #pragma unroll
;     for (int nt = 0; nt < 8; ++nt) rwv[nt] = *(const u32x2*)(rowp + C_R + h * 128 + nt * 16 + 4 * fq);
.LBB0_482:
	s_or_b64 exec, exec, s[10:11]
	v_add_f32_e32 v187, v68, v67
	v_add_f32_e32 v181, v187, v189
	v_add_f32_e32 v179, v181, v188
	v_add_f32_e32 v177, v179, v186
	v_add_f32_e32 v171, v177, v184
	v_add_f32_e32 v170, v171, v182
	v_add_f32_e32 v169, v170, v180
	v_add_f32_e32 v168, v169, v178
	v_add_f32_e32 v167, v168, v176
	v_add_f32_e32 v166, v167, v173
	v_add_f32_e32 v165, v166, v172
	s_waitcnt vmcnt(0)
	v_lshrrev_b32_e32 v240, 8, v228
	v_mul_u32_u24_e32 v240, 0x4800, v240
	v_add_u32_e32 v240, 0x17000, v240
	v_bfe_u32 v241, v228, 6, 2
	v_lshlrev_b32_e32 v241, 5, v241
	v_bfe_u32 v244, v228, 3, 3
	v_add_u32_e32 v241, v241, v244
	v_mul_u32_u24_e32 v241, 0x90, v241
	v_and_b32_e32 v244, 7, v228
	v_lshl_add_u32 v241, v244, 4, v241
	v_add_u32_e32 v244, v240, v241
	v_and_b32_e32 v241, 15, v228
	v_mul_u32_u24_e32 v241, 0x90, v241
	v_bfe_u32 v245, v228, 4, 2
	v_lshl_add_u32 v241, v245, 4, v241
	v_add_u32_e32 v245, v240, v241
	ds_write_b128 v244, v[204:207]
	ds_write_b128 v244, v[208:211] offset:1152
	ds_write_b128 v244, v[212:215] offset:2304
	ds_write_b128 v244, v[216:219] offset:3456
	v_lshrrev_b32_e32 v240, 8, v228
	v_mul_u32_u24_e32 v240, 0xb800, v240
	v_add_u32_e32 v240, 0x6c00, v240
	v_bfe_u32 v241, v228, 6, 2
	v_mul_u32_u24_e32 v241, 0x1100, v241
	v_add_u32_e32 v240, v240, v241
	v_bfe_u32 v241, v228, 4, 2
	v_mul_u32_u24_e32 v242, 0x110, v241
	v_and_b32_e32 v243, 15, v228
	v_lshl_add_u32 v242, v243, 4, v242
	v_add_u32_e32 v246, v240, v242
	v_mul_u32_u24_e32 v242, 0x110, v243
	v_lshl_add_u32 v242, v241, 3, v242
	v_add_u32_e32 v247, v240, v242
	ds_write_b128 v246, v[50:53]
	ds_write_b128 v246, v[54:57] offset:1088
	ds_write_b128 v246, v[58:61] offset:2176
	ds_write_b128 v246, v[62:65] offset:3264
	s_waitcnt lgkmcnt(0)
	ds_read_b64 v[98:99], v247
	ds_read_b64 v[96:97], v247 offset:32
	ds_read_b64 v[94:95], v247 offset:64
	ds_read_b64 v[92:93], v247 offset:96
	ds_read_b64 v[90:91], v247 offset:128
	ds_read_b64 v[88:89], v247 offset:160
	ds_read_b64 v[86:87], v247 offset:192
	ds_read_b64 v[84:85], v247 offset:224
	s_waitcnt lgkmcnt(0)
	v_mul_i32_i24_e32 v69, 0xb800, v160
	v_add_f32_e32 v164, v165, v175
	v_add_f32_e32 v163, v164, v174
	v_add_u32_e32 v67, 0, v69
	v_add_f32_e32 v162, v163, v183
	v_lshl_add_u32 v160, v149, 2, v67
	v_add_f32_e32 v69, v162, v185
	v_lshl_add_u32 v172, v74, 8, v160
	ds_write_b32 v172, v69 offset:46080
	s_waitcnt lgkmcnt(0)
	s_barrier
	ds_read2st64_b32 v[172:173], v160 offset0:180 offset1:181
	ds_read_b32 v160, v160 offset:46592
	v_cmp_gt_u32_sdwa s[74:75], v71, v237 src0_sel:BYTE_0 src1_sel:DWORD
	s_movk_i32 s10, 0x7f
	s_waitcnt lgkmcnt(1)
	v_add_f32_e32 v172, 0, v172
	v_cndmask_b32_e64 v172, 0, v172, s[74:75]
	v_add_f32_e32 v173, v173, v172
	v_cmp_gt_u32_sdwa s[74:75], v71, s10 src0_sel:BYTE_0 src1_sel:DWORD
	s_nop 1
	v_cndmask_b32_e64 v172, v172, v173, s[74:75]
	s_waitcnt lgkmcnt(0)
	v_add_f32_e32 v160, v160, v172
	v_cmp_eq_u32_e64 s[74:75], 3, v74
	v_mov_b32_e32 v173, 0
	s_nop 0
	v_cndmask_b32_e64 v160, v172, v160, s[74:75]
	v_add_f32_e32 v68, v68, v160
	v_mov_b32_e32 v172, 0
	s_and_saveexec_b64 s[10:11], s[40:41]
	v_mul_f32_e32 v173, 0x3fb8aa3b, v68
	v_exp_f32_e32 v173, v173
	v_lshlrev_b32_e32 v161, 16, v161
	v_mul_f32_e32 v161, 0x3e000000, v161
	v_mul_f32_e32 v161, v161, v173
	v_cvt_pk_bf16_f32 v173, v161, s0
	s_or_b64 exec, exec, s[10:11]
	v_mul_f32_e32 v68, 0xbfb8aa3b, v68
	v_exp_f32_e32 v174, v68
	v_lshl_add_u32 v68, v149, 1, v67
	v_lshlrev_b32_e32 v149, 16, v159
	s_movk_i32 s10, 0x900
	v_mul_f32_e32 v149, v174, v149
	v_add_f32_e32 v161, v187, v160
	v_cvt_pk_bf16_f32 v149, v149, s0
	v_mad_u32_u24 v159, v74, s10, v68
	v_cndmask_b32_e64 v149, 0, v149, s[40:41]
	ds_write_b16 v159, v173
	ds_write_b16 v159, v149 offset:9216
	s_and_saveexec_b64 s[10:11], s[42:43]
	v_mul_f32_e32 v149, 0x3fb8aa3b, v161
	v_exp_f32_e32 v149, v149
	v_lshlrev_b32_e32 v158, 16, v158
	v_mul_f32_e32 v158, 0x3e000000, v158
	v_mul_f32_e32 v149, v158, v149
	v_cvt_pk_bf16_f32 v172, v149, s0
	s_or_b64 exec, exec, s[10:11]
	v_mul_f32_e32 v149, 0xbfb8aa3b, v161
	v_exp_f32_e32 v149, v149
	v_lshlrev_b32_e32 v157, 16, v157
	v_mul_u32_u24_e32 v159, 0x900, v74
	v_add_u32_e32 v68, v68, v159
	v_mul_f32_e32 v149, v149, v157
	v_cvt_pk_bf16_f32 v149, v149, s0
	v_cndmask_b32_e64 v149, 0, v149, s[42:43]
	v_add_f32_e32 v158, v181, v160
	ds_write_b16 v68, v172 offset:144
	ds_write_b16 v68, v149 offset:9360
	v_mov_b32_e32 v149, 0
	v_mov_b32_e32 v157, 0
	s_and_saveexec_b64 s[10:11], s[44:45]
	v_mul_f32_e32 v157, 0x3fb8aa3b, v158
	v_exp_f32_e32 v157, v157
	v_lshlrev_b32_e32 v150, 16, v150
	v_mul_f32_e32 v150, 0x3e000000, v150
	v_mul_f32_e32 v150, v150, v157
	v_cvt_pk_bf16_f32 v157, v150, s0
	s_or_b64 exec, exec, s[10:11]
	v_mul_f32_e32 v150, 0xbfb8aa3b, v158
	v_exp_f32_e32 v158, v150
	v_lshlrev_b32_e32 v148, 16, v148
	v_add_f32_e32 v150, v179, v160
	v_mul_f32_e32 v148, v158, v148
	v_cvt_pk_bf16_f32 v148, v148, s0
	v_cndmask_b32_e64 v148, 0, v148, s[44:45]
	ds_write_b16 v68, v157 offset:288
	ds_write_b16 v68, v148 offset:9504
	s_and_saveexec_b64 s[10:11], s[46:47]
	v_mul_f32_e32 v148, 0x3fb8aa3b, v150
	v_exp_f32_e32 v148, v148
	v_lshlrev_b32_e32 v149, 16, v156
	v_mul_f32_e32 v149, 0x3e000000, v149
	v_mul_f32_e32 v148, v149, v148
	v_cvt_pk_bf16_f32 v149, v148, s0
	s_or_b64 exec, exec, s[10:11]
	v_mul_f32_e32 v148, 0xbfb8aa3b, v150
	v_exp_f32_e32 v148, v148
	v_lshlrev_b32_e32 v152, 16, v152
	v_add_f32_e32 v150, v177, v160
	ds_write_b16 v68, v149 offset:432
	v_mul_f32_e32 v148, v148, v152
	v_cvt_pk_bf16_f32 v148, v148, s0
	v_cndmask_b32_e64 v148, 0, v148, s[46:47]
	ds_write_b16 v68, v148 offset:9648
	v_mov_b32_e32 v148, 0
	v_mov_b32_e32 v149, 0
; #define LAS __attribute__((address_space(3)))
; __device__ __forceinline__ float bf2f(bf16_t b) { return __uint_as_float(((unsigned)b) << 16); }
; __device__ __forceinline__ bf16_t f2bf(float f) { return (bf16_t)(cvt_pk_bf16(f, 0.f) & 0xffffu); }
; __device__ void gla3_item(const Params& p, int l, int item, LAS unsigned char* lds) {
;     ...
;     for (int i = 0; i < 16; ++i) { const int rbi = n * 64 + seg * 16 + i, row = seg * 16 + i;
;         const float qv = rbi < TB ? bf2f(L.xq[i]) * 0.125f * __expf(bc[i]) : 0.f, kv = rbi < TB ? bf2f(L.xk[i]) * __expf(-bc[i]) : 0.f;
;         *(LAS bf16_t*)(hl + GL_QD + row * 144 + dk * 2) = f2bf(qv); *(LAS bf16_t*)(hl + GL_KI + row * 144 + dk * 2) = f2bf(kv); }
	s_and_saveexec_b64 s[10:11], s[48:49]
	v_mul_f32_e32 v149, 0x3fb8aa3b, v150
	v_exp_f32_e32 v149, v149
	v_lshlrev_b32_e32 v147, 16, v147
	v_mul_f32_e32 v147, 0x3e000000, v147
	v_mul_f32_e32 v147, v147, v149
	v_cvt_pk_bf16_f32 v149, v147, s0
	s_or_b64 exec, exec, s[10:11]
	v_mul_f32_e32 v147, 0xbfb8aa3b, v150
	v_exp_f32_e32 v150, v147
	v_lshlrev_b32_e32 v145, 16, v145
	v_add_f32_e32 v147, v171, v160
	v_mul_f32_e32 v145, v150, v145
	v_cvt_pk_bf16_f32 v145, v145, s0
	v_cndmask_b32_e64 v145, 0, v145, s[48:49]
	ds_write_b16 v68, v149 offset:576
	ds_write_b16 v68, v145 offset:9792
	s_and_saveexec_b64 s[10:11], s[50:51]
	v_mul_f32_e32 v145, 0x3fb8aa3b, v147
	v_exp_f32_e32 v145, v145
	v_lshlrev_b32_e32 v143, 16, v143
	v_mul_f32_e32 v143, 0x3e000000, v143
	v_mul_f32_e32 v143, v143, v145
	v_cvt_pk_bf16_f32 v148, v143, s0
	s_or_b64 exec, exec, s[10:11]
	v_mul_f32_e32 v143, 0xbfb8aa3b, v147
	v_exp_f32_e32 v143, v143
	v_lshlrev_b32_e32 v146, 16, v146
	v_add_f32_e32 v145, v170, v160
	ds_write_b16 v68, v148 offset:720
	v_mul_f32_e32 v143, v143, v146
	v_cvt_pk_bf16_f32 v143, v143, s0
	v_cndmask_b32_e64 v143, 0, v143, s[50:51]
	ds_write_b16 v68, v143 offset:9936
	v_mov_b32_e32 v143, 0
	v_mov_b32_e32 v146, 0
	s_and_saveexec_b64 s[10:11], s[52:53]
	v_mul_f32_e32 v146, 0x3fb8aa3b, v145
	v_exp_f32_e32 v146, v146
	v_lshlrev_b32_e32 v140, 16, v140
	v_mul_f32_e32 v140, 0x3e000000, v140
	v_mul_f32_e32 v140, v140, v146
	v_cvt_pk_bf16_f32 v146, v140, s0
	s_or_b64 exec, exec, s[10:11]
	v_mul_f32_e32 v140, 0xbfb8aa3b, v145
	v_exp_f32_e32 v145, v140
	v_lshlrev_b32_e32 v138, 16, v138
	v_add_f32_e32 v140, v169, v160
	v_mul_f32_e32 v138, v145, v138
	v_cvt_pk_bf16_f32 v138, v138, s0
	v_cndmask_b32_e64 v138, 0, v138, s[52:53]
	ds_write_b16 v68, v146 offset:864
	ds_write_b16 v68, v138 offset:10080
	s_and_saveexec_b64 s[10:11], s[54:55]
	v_mul_f32_e32 v138, 0x3fb8aa3b, v140
	v_exp_f32_e32 v138, v138
	v_lshlrev_b32_e32 v136, 16, v136
	v_mul_f32_e32 v136, 0x3e000000, v136
	v_mul_f32_e32 v136, v136, v138
	v_cvt_pk_bf16_f32 v143, v136, s0
	s_or_b64 exec, exec, s[10:11]
	v_mul_f32_e32 v136, 0xbfb8aa3b, v140
	v_exp_f32_e32 v138, v136
	v_lshlrev_b32_e32 v134, 16, v134
	v_add_f32_e32 v136, v168, v160
	ds_write_b16 v68, v143 offset:1008
	v_mul_f32_e32 v134, v138, v134
	v_cvt_pk_bf16_f32 v134, v134, s0
	v_cndmask_b32_e64 v134, 0, v134, s[54:55]
	ds_write_b16 v68, v134 offset:10224
	v_mov_b32_e32 v134, 0
	v_mov_b32_e32 v138, 0
	s_and_saveexec_b64 s[10:11], s[56:57]
	v_mul_f32_e32 v138, 0x3fb8aa3b, v136
	v_exp_f32_e32 v138, v138
	v_lshlrev_b32_e32 v137, 16, v137
	v_mul_f32_e32 v137, 0x3e000000, v137
	v_mul_f32_e32 v137, v137, v138
	v_cvt_pk_bf16_f32 v138, v137, s0
	s_or_b64 exec, exec, s[10:11]
	v_mul_f32_e32 v136, 0xbfb8aa3b, v136
	v_exp_f32_e32 v137, v136
	v_lshlrev_b32_e32 v135, 16, v135
	v_add_f32_e32 v136, v167, v160
	v_mul_f32_e32 v135, v137, v135
	v_cvt_pk_bf16_f32 v135, v135, s0
	v_cndmask_b32_e64 v135, 0, v135, s[56:57]
	ds_write_b16 v68, v138 offset:1152
	ds_write_b16 v68, v135 offset:10368
	s_and_saveexec_b64 s[10:11], s[58:59]
	v_mul_f32_e32 v134, 0x3fb8aa3b, v136
	v_exp_f32_e32 v134, v134
	v_lshlrev_b32_e32 v133, 16, v133
	v_mul_f32_e32 v133, 0x3e000000, v133
	v_mul_f32_e32 v133, v133, v134
	v_cvt_pk_bf16_f32 v134, v133, s0
	s_or_b64 exec, exec, s[10:11]
	v_mul_f32_e32 v133, 0xbfb8aa3b, v136
	v_exp_f32_e32 v135, v133
	v_lshlrev_b32_e32 v128, 16, v128
	v_add_f32_e32 v133, v166, v160
	ds_write_b16 v68, v134 offset:1296
	v_mul_f32_e32 v128, v135, v128
	v_cvt_pk_bf16_f32 v128, v128, s0
	v_cndmask_b32_e64 v128, 0, v128, s[58:59]
	ds_write_b16 v68, v128 offset:10512
	v_mov_b32_e32 v128, 0
	v_mov_b32_e32 v134, 0
	s_and_saveexec_b64 s[10:11], s[60:61]
	v_mul_f32_e32 v134, 0x3fb8aa3b, v133
	v_exp_f32_e32 v134, v134
	v_lshlrev_b32_e32 v125, 16, v125
	v_mul_f32_e32 v125, 0x3e000000, v125
	v_mul_f32_e32 v125, v125, v134
	v_cvt_pk_bf16_f32 v134, v125, s0
	s_or_b64 exec, exec, s[10:11]
	v_mul_f32_e32 v125, 0xbfb8aa3b, v133
	v_exp_f32_e32 v133, v125
	v_lshlrev_b32_e32 v121, 16, v121
	v_add_f32_e32 v125, v165, v160
	v_mul_f32_e32 v121, v133, v121
	v_cvt_pk_bf16_f32 v121, v121, s0
	v_cndmask_b32_e64 v121, 0, v121, s[60:61]
	ds_write_b16 v68, v134 offset:1440
	ds_write_b16 v68, v121 offset:10656
	s_and_saveexec_b64 s[10:11], s[62:63]
	v_mul_f32_e32 v121, 0x3fb8aa3b, v125
	v_exp_f32_e32 v121, v121
	v_lshlrev_b32_e32 v127, 16, v127
	v_mul_f32_e32 v127, 0x3e000000, v127
	v_mul_f32_e32 v121, v127, v121
	v_cvt_pk_bf16_f32 v128, v121, s0
	s_or_b64 exec, exec, s[10:11]
	v_mul_f32_e32 v121, 0xbfb8aa3b, v125
	v_exp_f32_e32 v121, v121
	v_lshlrev_b32_e32 v126, 16, v126
	v_add_f32_e32 v125, v164, v160
	ds_write_b16 v68, v128 offset:1584
	v_mul_f32_e32 v121, v121, v126
	v_cvt_pk_bf16_f32 v121, v121, s0
	v_cndmask_b32_e64 v121, 0, v121, s[62:63]
	ds_write_b16 v68, v121 offset:10800
	v_mov_b32_e32 v121, 0
	v_mov_b32_e32 v126, 0
	s_and_saveexec_b64 s[10:11], s[64:65]
	v_mul_f32_e32 v126, 0x3fb8aa3b, v125
	v_exp_f32_e32 v126, v126
	v_lshlrev_b32_e32 v119, 16, v119
	v_mul_f32_e32 v119, 0x3e000000, v119
	v_mul_f32_e32 v119, v119, v126
	v_cvt_pk_bf16_f32 v126, v119, s0
	s_or_b64 exec, exec, s[10:11]
	v_mul_f32_e32 v119, 0xbfb8aa3b, v125
	v_exp_f32_e32 v125, v119
	v_lshlrev_b32_e32 v110, 16, v110
	v_add_f32_e32 v119, v163, v160
	v_mul_f32_e32 v110, v125, v110
	v_cvt_pk_bf16_f32 v110, v110, s0
	v_cndmask_b32_e64 v110, 0, v110, s[64:65]
	ds_write_b16 v68, v126 offset:1728
	ds_write_b16 v68, v110 offset:10944
	s_and_saveexec_b64 s[10:11], s[66:67]
	v_mul_f32_e32 v110, 0x3fb8aa3b, v119
	v_exp_f32_e32 v110, v110
	v_lshlrev_b32_e32 v106, 16, v106
	v_mul_f32_e32 v106, 0x3e000000, v106
	v_mul_f32_e32 v106, v106, v110
; #define LAS __attribute__((address_space(3)))
; __device__ __forceinline__ float bf2f(bf16_t b) { return __uint_as_float(((unsigned)b) << 16); }
; __device__ __forceinline__ bf16_t f2bf(float f) { return (bf16_t)(cvt_pk_bf16(f, 0.f) & 0xffffu); }
; __device__ __forceinline__ void gla_store_vT(const GlaLoads& L, int n, int t4, LAS unsigned char* hl) {
; #pragma unroll
;     for (int q = 0; q < 4; ++q) { const int task = t4 + 256 * q, dv = task & 127, rg = task >> 7; unsigned v[8];
; #pragma unroll
;         for (int j = 0; j < 8; ++j) { const int rb = n * 64 + rg * 8 + j; v[j] = rb < TB ? (unsigned)L.vv[q][j] : 0u; }
;         u32x4 w; w.x = v[0] | (v[1] << 16); w.y = v[2] | (v[3] << 16); w.z = v[4] | (v[5] << 16); w.w = v[6] | (v[7] << 16);
;         *(LAS u32x4*)(hl + GL_VT + dv * 144 + rg * 16) = w; }
; }
; __device__ void gla3_item(const Params& p, int l, int item, LAS unsigned char* lds) {
;     ...
;     for (int i = 0; i < 16; ++i) { const int rbi = n * 64 + seg * 16 + i, row = seg * 16 + i;
;         const float qv = rbi < TB ? bf2f(L.xq[i]) * 0.125f * __expf(bc[i]) : 0.f, kv = rbi < TB ? bf2f(L.xk[i]) * __expf(-bc[i]) : 0.f;
;         *(LAS bf16_t*)(hl + GL_QD + row * 144 + dk * 2) = f2bf(qv); *(LAS bf16_t*)(hl + GL_KI + row * 144 + dk * 2) = f2bf(kv); }
;     gla_store_vT(L, n, t4, hl);
	v_cvt_pk_bf16_f32 v121, v106, s0
	s_or_b64 exec, exec, s[10:11]
	v_mul_f32_e32 v106, 0xbfb8aa3b, v119
	v_exp_f32_e32 v106, v106
	v_lshlrev_b32_e32 v112, 16, v112
	v_add_f32_e32 v110, v162, v160
	ds_write_b16 v68, v121 offset:1872
	v_mul_f32_e32 v106, v106, v112
	v_cvt_pk_bf16_f32 v106, v106, s0
	v_cndmask_b32_e64 v106, 0, v106, s[66:67]
	ds_write_b16 v68, v106 offset:11088
	v_mov_b32_e32 v106, 0
	v_mov_b32_e32 v112, 0
	s_and_saveexec_b64 s[10:11], s[70:71]
	v_mul_f32_e32 v112, 0x3fb8aa3b, v110
	v_exp_f32_e32 v112, v112
	v_lshlrev_b32_e32 v104, 16, v104
	v_mul_f32_e32 v104, 0x3e000000, v104
	v_mul_f32_e32 v104, v104, v112
	v_cvt_pk_bf16_f32 v112, v104, s0
	s_or_b64 exec, exec, s[10:11]
	v_mul_f32_e32 v104, 0xbfb8aa3b, v110
	v_exp_f32_e32 v104, v104
	v_lshlrev_b32_e32 v81, 16, v81
	v_add_f32_e32 v69, v69, v160
	v_mul_f32_e32 v81, v104, v81
	v_cvt_pk_bf16_f32 v81, v81, s0
	v_cndmask_b32_e64 v81, 0, v81, s[70:71]
	ds_write_b16 v68, v112 offset:2016
	ds_write_b16 v68, v81 offset:11232
	s_and_saveexec_b64 s[10:11], s[68:69]
	v_mul_f32_e32 v81, 0x3fb8aa3b, v69
	v_exp_f32_e32 v81, v81
	v_lshlrev_b32_e32 v78, 16, v78
	v_mul_f32_e32 v78, 0x3e000000, v78
	v_mul_f32_e32 v78, v78, v81
	v_cvt_pk_bf16_f32 v106, v78, s0
	s_or_b64 exec, exec, s[10:11]
	v_mul_f32_e32 v69, 0xbfb8aa3b, v69
	v_exp_f32_e32 v69, v69
	v_lshlrev_b32_e32 v73, 16, v73
	s_movk_i32 s10, 0x1020
	v_and_b32_e32 v78, 0xffff, v114
	v_mul_f32_e32 v69, v69, v73
	v_cvt_pk_bf16_f32 v69, v69, s0
	v_cndmask_b32_e64 v69, 0, v69, s[68:69]
	ds_write_b16 v68, v106 offset:2160
	ds_write_b16 v68, v69 offset:11376
	v_lshrrev_b32_sdwa v68, v238, v71 dst_sel:DWORD dst_unused:UNUSED_PAD src0_sel:DWORD src1_sel:BYTE_0
	v_lshl_or_b32 v69, v68, 3, v70
	v_cmp_gt_i32_e64 s[40:41], s10, v69
	v_or_b32_e32 v73, 1, v69
	v_and_b32_e32 v81, 0xffff, v115
	v_cndmask_b32_e64 v71, 0, v78, s[40:41]
	v_lshlrev_b32_e32 v78, 16, v102
	v_cmp_gt_i32_e64 s[40:41], s10, v73
	v_lshlrev_b32_e32 v101, 16, v101
	v_and_b32_e32 v104, 0xffff, v116
	v_cndmask_b32_e64 v73, 0, v78, s[40:41]
	v_or_b32_e32 v78, 2, v69
	v_cmp_gt_i32_e64 s[40:41], s10, v78
	v_or_b32_e32 v78, 3, v69
	v_lshlrev_b32_e32 v80, 16, v80
	v_cndmask_b32_e64 v81, 0, v81, s[40:41]
	v_cmp_gt_i32_e64 s[40:41], s10, v78
	v_or_b32_e32 v78, 4, v69
	v_and_b32_e32 v110, 0xffff, v117
	v_cndmask_b32_e64 v101, 0, v101, s[40:41]
	v_cmp_gt_i32_e64 s[40:41], s10, v78
	v_or_b32_e32 v78, 5, v69
	s_movk_i32 s11, 0x90
	v_cndmask_b32_e64 v102, 0, v104, s[40:41]
	v_cmp_gt_i32_e64 s[40:41], s10, v78
	v_or_b32_e32 v78, 6, v69
	v_or_b32_e32 v69, 7, v69
	v_cndmask_b32_e64 v80, 0, v80, s[40:41]
	v_cmp_gt_i32_e64 s[40:41], s10, v78
	v_lshlrev_b32_e32 v78, 16, v79
	v_mad_u32_u24 v72, v72, s11, v67
	v_cndmask_b32_e64 v104, 0, v110, s[40:41]
	v_cmp_gt_i32_e64 s[40:41], s10, v69
	v_or_b32_e32 v79, v101, v81
	v_or_b32_e32 v80, v80, v102
	v_cndmask_b32_e64 v69, 0, v78, s[40:41]
	v_or_b32_e32 v78, v73, v71
	v_or_b32_e32 v81, v69, v104
	v_lshl_add_u32 v69, v68, 4, v72
	ds_write_b128 v69, v[78:81] offset:27648
	v_or_b32_e32 v69, 2, v68
	v_lshl_or_b32 v71, v69, 3, v70
	v_and_b32_e32 v112, 0xffff, v129
	v_cmp_gt_i32_e64 s[40:41], s10, v71
	v_or_b32_e32 v78, 1, v71
	v_lshlrev_b32_e32 v79, 16, v108
	v_cndmask_b32_e64 v73, 0, v112, s[40:41]
	v_cmp_gt_i32_e64 s[40:41], s10, v78
	v_and_b32_e32 v114, 0xffff, v130
	v_or_b32_e32 v80, 3, v71
	v_cndmask_b32_e64 v78, 0, v79, s[40:41]
	v_or_b32_e32 v79, 2, v71
	v_cmp_gt_i32_e64 s[40:41], s10, v79
	v_lshlrev_b32_e32 v81, 16, v107
	v_and_b32_e32 v115, 0xffff, v131
	v_cndmask_b32_e64 v79, 0, v114, s[40:41]
	v_cmp_gt_i32_e64 s[40:41], s10, v80
	v_or_b32_e32 v101, 5, v71
	v_lshlrev_b32_e32 v102, 16, v105
	v_cndmask_b32_e64 v80, 0, v81, s[40:41]
	v_or_b32_e32 v81, 4, v71
	v_cmp_gt_i32_e64 s[40:41], s10, v81
	v_and_b32_e32 v116, 0xffff, v132
	v_lshlrev_b32_e32 v103, 16, v103
	v_cndmask_b32_e64 v81, 0, v115, s[40:41]
	v_cmp_gt_i32_e64 s[40:41], s10, v101
	v_or_b32_e32 v78, v78, v73
	v_or_b32_e32 v79, v80, v79
	v_cndmask_b32_e64 v101, 0, v102, s[40:41]
	v_or_b32_e32 v102, 6, v71
	v_cmp_gt_i32_e64 s[40:41], s10, v102
	v_or_b32_e32 v71, 7, v71
	v_or_b32_e32 v80, v101, v81
	v_cndmask_b32_e64 v102, 0, v116, s[40:41]
	v_cmp_gt_i32_e64 s[40:41], s10, v71
	v_lshl_add_u32 v69, v69, 4, v72
	v_and_b32_e32 v117, 0xffff, v139
	v_cndmask_b32_e64 v71, 0, v103, s[40:41]
	v_or_b32_e32 v81, v71, v102
	ds_write_b128 v69, v[78:81] offset:27648
	v_or_b32_e32 v69, 4, v68
	v_lshl_or_b32 v71, v69, 3, v70
	v_cmp_gt_i32_e64 s[40:41], s10, v71
	v_or_b32_e32 v78, 1, v71
	v_lshlrev_b32_e32 v79, 16, v118
	v_cndmask_b32_e64 v73, 0, v117, s[40:41]
; #define LAS __attribute__((address_space(3)))
; __device__ __forceinline__ unsigned cvt_pk_bf16(float lo, float hi) { const f32x2 f = {lo, hi}; const bf16n2 v = __builtin_convertvector(f, bf16n2); return __builtin_bit_cast(unsigned, v); }
; __device__ __forceinline__ f32x4 mfma16(bf16x8 colfrag, bf16x8 rowfrag, f32x4 acc) { return __builtin_amdgcn_mfma_f32_16x16x32_bf16(colfrag, rowfrag, acc, 0, 0, 0); }
; __device__ __forceinline__ void gla_store_vT(const GlaLoads& L, int n, int t4, LAS unsigned char* hl) {
; #pragma unroll
;     for (int q = 0; q < 4; ++q) { const int task = t4 + 256 * q, dv = task & 127, rg = task >> 7; unsigned v[8];
; #pragma unroll
;         for (int j = 0; j < 8; ++j) { const int rb = n * 64 + rg * 8 + j; v[j] = rb < TB ? (unsigned)L.vv[q][j] : 0u; }
;         u32x4 w; w.x = v[0] | (v[1] << 16); w.y = v[2] | (v[3] << 16); w.z = v[4] | (v[5] << 16); w.w = v[6] | (v[7] << 16);
;         *(LAS u32x4*)(hl + GL_VT + dv * 144 + rg * 16) = w; }
; }
; __device__ void gla3_item(const Params& p, int l, int item, LAS unsigned char* lds) {
;     ...
;     gla_store_vT(L, n, t4, hl);
;     __syncthreads();
;     bf16x8 qf[2];
; #pragma unroll
;     for (int ks = 0; ks < 2; ++ks) qf[ks] = *(const LAS bf16x8*)(hl + GL_QD + (wv * 16 + fr) * 144 + (ks * 32 + fq * 8) * 2);
; #pragma unroll
;     for (int st = 0; st < 4; ++st) { f32x4 acc = (f32x4){0.f, 0.f, 0.f, 0.f};
;         if (st <= wv) {
; #pragma unroll
;             for (int ks = 0; ks < 2; ++ks) { const bf16x8 cf = *(const LAS bf16x8*)(hl + GL_KI + (st * 16 + fr) * 144 + (ks * 32 + fq * 8) * 2); acc = mfma16(cf, qf[ks], acc); }
;             const int c = wv * 16 + fr, s0 = st * 16 + 4 * fq;
; #pragma unroll
;             for (int r = 0; r < 4; ++r) if (s0 + r > c) acc[r] = 0.f;
;         }
;         u32x2 w; w.x = cvt_pk_bf16(acc[0], acc[1]); w.y = cvt_pk_bf16(acc[2], acc[3]);
;         *(LAS u32x2*)(hl + GL_P + (wv * 16 + fr) * 144 + (st * 16 + 4 * fq) * 2) = w; }
	v_cmp_gt_i32_e64 s[40:41], s10, v78
	v_and_b32_e32 v119, 0xffff, v141
	v_or_b32_e32 v80, 3, v71
	v_cndmask_b32_e64 v78, 0, v79, s[40:41]
	v_or_b32_e32 v79, 2, v71
	v_cmp_gt_i32_e64 s[40:41], s10, v79
	v_lshlrev_b32_e32 v81, 16, v113
	v_and_b32_e32 v121, 0xffff, v142
	v_cndmask_b32_e64 v79, 0, v119, s[40:41]
	v_cmp_gt_i32_e64 s[40:41], s10, v80
	v_or_b32_e32 v101, 5, v71
	v_lshlrev_b32_e32 v102, 16, v111
	v_cndmask_b32_e64 v80, 0, v81, s[40:41]
	v_or_b32_e32 v81, 4, v71
	v_cmp_gt_i32_e64 s[40:41], s10, v81
	v_and_b32_e32 v125, 0xffff, v144
	v_lshlrev_b32_e32 v103, 16, v109
	v_cndmask_b32_e64 v81, 0, v121, s[40:41]
	v_cmp_gt_i32_e64 s[40:41], s10, v101
	v_or_b32_e32 v78, v78, v73
	v_or_b32_e32 v73, 6, v68
	v_cndmask_b32_e64 v101, 0, v102, s[40:41]
	v_or_b32_e32 v102, 6, v71
	v_cmp_gt_i32_e64 s[40:41], s10, v102
	v_or_b32_e32 v71, 7, v71
	v_lshl_or_b32 v68, v73, 3, v70
	v_cndmask_b32_e64 v102, 0, v125, s[40:41]
	v_cmp_gt_i32_e64 s[40:41], s10, v71
	v_and_b32_e32 v126, 0xffff, v154
	v_or_b32_e32 v79, v80, v79
	v_cndmask_b32_e64 v71, 0, v103, s[40:41]
	v_or_b32_e32 v80, v101, v81
	v_or_b32_e32 v81, v71, v102
	v_lshl_add_u32 v69, v69, 4, v72
	v_cmp_gt_i32_e64 s[40:41], s10, v68
	v_or_b32_e32 v70, 1, v68
	ds_write_b128 v69, v[78:81] offset:27648
	v_cndmask_b32_e64 v69, 0, v126, s[40:41]
	v_lshlrev_b32_e32 v71, 16, v124
	v_cmp_gt_i32_e64 s[40:41], s10, v70
	v_and_b32_e32 v127, 0xffff, v155
	v_or_b32_e32 v78, 3, v68
	v_cndmask_b32_e64 v70, 0, v71, s[40:41]
	v_or_b32_e32 v71, 2, v68
	v_cmp_gt_i32_e64 s[40:41], s10, v71
	v_lshlrev_b32_e32 v79, 16, v123
	v_and_b32_e32 v128, 0xffff, v151
	v_cndmask_b32_e64 v71, 0, v127, s[40:41]
	v_cmp_gt_i32_e64 s[40:41], s10, v78
	v_or_b32_e32 v80, 5, v68
	v_lshlrev_b32_e32 v81, 16, v122
	v_cndmask_b32_e64 v78, 0, v79, s[40:41]
	v_or_b32_e32 v79, 4, v68
	v_cmp_gt_i32_e64 s[40:41], s10, v79
	v_and_b32_e32 v129, 0xffff, v153
	v_lshlrev_b32_e32 v101, 16, v120
	v_cndmask_b32_e64 v79, 0, v128, s[40:41]
	v_cmp_gt_i32_e64 s[40:41], s10, v80
	v_lshl_add_u32 v72, v73, 4, v72
	v_add_u32_e32 v103, v67, v66
	v_cndmask_b32_e64 v80, 0, v81, s[40:41]
	v_or_b32_e32 v81, 6, v68
	v_cmp_gt_i32_e64 s[40:41], s10, v81
	v_or_b32_e32 v68, 7, v68
	v_mad_u32_u24 v108, v77, s11, v67
	v_cndmask_b32_e64 v81, 0, v129, s[40:41]
	v_cmp_gt_i32_e64 s[40:41], s10, v68
	v_or_b32_e32 v68, v70, v69
	v_or_b32_e32 v69, v78, v71
	v_cndmask_b32_e64 v101, 0, v101, s[40:41]
	v_or_b32_e32 v70, v80, v79
	v_or_b32_e32 v71, v101, v81
	ds_write_b128 v72, v[68:71] offset:27648
	v_mad_u32_u24 v68, v75, s11, v103
	s_waitcnt lgkmcnt(0)
	s_barrier
	ds_read_b128 v[78:81], v68 offset:9216
	v_add_u32_e32 v102, v108, v66
	ds_read_b128 v[104:107], v68 offset:9280
	ds_read_b128 v[70:73], v102
	ds_read_b128 v[66:69], v102 offset:64
	s_waitcnt lgkmcnt(1)
	v_mfma_f32_16x16x32_bf16 v[78:81], v[78:81], v[70:73], 0
	v_lshlrev_b32_e32 v101, 2, v76
	v_add_u32_e32 v76, v108, v0
	v_mov_b32_e32 v0, s87
	s_waitcnt lgkmcnt(0)
	v_mfma_f32_16x16x32_bf16 v[78:81], v[104:107], v[66:69], v[78:81]
	v_cmp_gt_u32_e64 s[40:41], v101, v77
	v_or_b32_e32 v104, 2, v101
	v_mul_u32_u24_e32 v108, 0x90, v75
	v_or_b32_e32 v75, 3, v101
	s_nop 3
	v_cndmask_b32_e64 v0, v78, v0, s[40:41]
	v_cmp_lt_u32_e64 s[40:41], v101, v77
	s_nop 1
	v_cndmask_b32_e64 v0, v0, v78, s[40:41]
	v_cndmask_b32_e64 v78, 0, v79, s[40:41]
	v_cmp_le_u32_e64 s[40:41], v104, v77
	v_cvt_pk_bf16_f32 v78, v0, v78
	v_add_u32_e32 v0, v103, v108
	v_cndmask_b32_e64 v79, 0, v80, s[40:41]
	v_cmp_le_u32_e64 s[40:41], v75, v77
	v_mov_b32_e32 v80, 0
	s_nop 0
	v_cndmask_b32_e64 v75, 0, v81, s[40:41]
	v_cvt_pk_bf16_f32 v79, v79, v75
	ds_write_b64 v76, v[78:79] offset:18432
	v_cmp_ne_u32_e64 s[40:41], 0, v74
	v_mov_b32_e32 v75, 0
	v_mov_b32_e32 v78, 0
	v_mov_b32_e32 v79, 0
	v_mov_b32_e32 v81, 0
	s_and_saveexec_b64 s[10:11], s[40:41]
	s_cbranch_execz .LBB0_516
	ds_read_b128 v[78:81], v0 offset:11520
	ds_read_b128 v[104:107], v0 offset:11584
	v_or_b32_e32 v103, 16, v101
	v_cmp_gt_u32_e64 s[40:41], v103, v77
	v_or_b32_e32 v103, 17, v101
	s_waitcnt lgkmcnt(1)
	v_mfma_f32_16x16x32_bf16 v[78:81], v[78:81], v[70:73], 0
	s_waitcnt lgkmcnt(0)
	v_mfma_f32_16x16x32_bf16 v[78:81], v[104:107], v[66:69], v[78:81]
	v_mov_b32_e32 v104, s87
	s_nop 6
	v_cndmask_b32_e64 v78, v78, v104, s[40:41]
	v_cmp_le_u32_e64 s[40:41], v103, v77
	v_or_b32_e32 v103, 18, v101
	s_nop 0
	v_cndmask_b32_e64 v79, 0, v79, s[40:41]
	v_cmp_le_u32_e64 s[40:41], v103, v77
	v_or_b32_e32 v103, 19, v101
	s_nop 0
	v_cndmask_b32_e64 v80, 0, v80, s[40:41]
	v_cmp_le_u32_e64 s[40:41], v103, v77
	s_nop 1
	v_cndmask_b32_e64 v81, 0, v81, s[40:41]
